# P2b s5_sample index rotation: the 16 carry workgroups get 2 sample items instead of 3
# speedup vs baseline: 1.0016x; 1.0016x over previous
.LBB0_535:
	v_readlane_b32 s0, v250, 0
	s_lshl_b32 s15, s0, 3
	s_mov_b32 s65, s94
	s_mov_b32 s66, s15
	s_cmpk_lt_i32 s94, 0x80
	s_cbranch_scc1 .Ls5s_nobal
	s_sub_i32 s65, s94, 64
	s_cmp_ge_i32 s0, s65
	s_cselect_b32 s66, 0x1000, s15
	s_cbranch_scc1 .Ls5s_nobal
	s_sub_i32 s66, s15, 0x80
	s_cmp_lt_i32 s0, 16
	s_cbranch_scc0 .Ls5s_nobal
	s_lshl_b32 s66, s65, 3
	s_add_i32 s66, s66, s15
	s_sub_i32 s66, s66, 0x80
